# stick-breaking loop: causal tests against constants (one subtract per tile instead of 31 v_or), 7 ln2 steps write the consumer register directly
# baseline (speedup 1.0000x reference)
.LBB0_465:
	s_cmp_ge_i32 s23, s4
	s_cselect_b64 s[16:17], -1, 0
	s_or_b64 s[16:17], s[16:17], s[14:15]
	s_and_b64 vcc, exec, s[16:17]
	s_cbranch_vccnz .LBB0_467
	v_add3_u32 v130, s18, v192, v205
	ds_read_b128 v[64:67], v130 offset:8704
	ds_read_b128 v[132:135], v130 offset:8736
	v_or_b32_e32 v163, s23, v200
	v_sub_u32_e32 v248, v152, v163
	v_add3_u32 v207, s22, v204, v206
	s_waitcnt lgkmcnt(1)
	v_mfma_f32_32x32x16_bf16 v[66:81], v[64:67], v[82:85], 0
	s_waitcnt lgkmcnt(0)
	v_mfma_f32_32x32x16_bf16 v[66:81], v[132:135], v[86:89], v[66:81]
	ds_read_b128 v[132:135], v130 offset:8768
	ds_read_b128 v[136:139], v130 offset:8800
	s_waitcnt lgkmcnt(1)
	v_mfma_f32_32x32x16_bf16 v[66:81], v[132:135], v[90:93], v[66:81]
	s_waitcnt lgkmcnt(0)
	v_mfma_f32_32x32x16_bf16 v[66:81], v[136:139], v[94:97], v[66:81]
	ds_read_b128 v[132:135], v130 offset:8832
	ds_read_b128 v[136:139], v130 offset:8864
	s_waitcnt lgkmcnt(1)
	v_mfma_f32_32x32x16_bf16 v[66:81], v[132:135], v[98:101], v[66:81]
	s_waitcnt lgkmcnt(0)
	v_mfma_f32_32x32x16_bf16 v[66:81], v[136:139], v[102:105], v[66:81]
	ds_read_b128 v[132:135], v130 offset:8896
	ds_read_b128 v[136:139], v130 offset:8928
	ds_read_b128 v[208:211], v130 offset:224
	s_waitcnt lgkmcnt(2)
	v_mfma_f32_32x32x16_bf16 v[66:81], v[132:135], v[106:109], v[66:81]
	s_waitcnt lgkmcnt(1)
	v_mfma_f32_32x32x16_bf16 v[66:81], v[136:139], v[110:113], v[66:81]
	s_nop 11
	v_mov_b32_e32 v64, v66
	v_mov_b32_e32 v65, v68
	v_mov_b32_e32 v68, v67
	v_pk_mul_f32 v[132:133], v[64:65], s[68:69] op_sel_hi:[1,0]
	v_mov_b32_e32 v66, v70
	v_pk_mul_f32 v[134:135], v[68:69], s[68:69] op_sel_hi:[1,0]
	v_mul_f32_e64 v70, |v132|, s54
	v_mov_b32_e32 v67, v72
	v_mul_f32_e64 v72, |v134|, s54
	v_exp_f32_e32 v70, v70
	v_mul_f32_e64 v131, |v133|, s54
	v_exp_f32_e32 v72, v72
	v_mul_f32_e64 v138, |v135|, s54
	v_exp_f32_e32 v131, v131
	v_pk_mul_f32 v[136:137], v[66:67], s[68:69] op_sel_hi:[1,0]
	v_exp_f32_e32 v138, v138
	v_mul_f32_e64 v139, |v136|, s54
	v_add_f32_e32 v70, 1.0, v70
	v_exp_f32_e32 v139, v139
	v_add_f32_e32 v72, 1.0, v72
	v_add_f32_e32 v131, 1.0, v131
	v_add_f32_e32 v138, 1.0, v138
	v_log_f32_e32 v70, v70
	v_add_f32_e32 v139, 1.0, v139
	v_log_f32_e32 v72, v72
	v_log_f32_e32 v131, v131
	v_log_f32_e32 v138, v138
	v_mov_b32_e32 v142, v139
	v_mul_f32_e32 v139, 0x3f317217, v70
	v_mul_f32_e32 v140, 0x3f317217, v72
	v_fma_f32 v139, v70, s86, -v139
	v_mul_f32_e32 v141, 0x3f317217, v131
	v_fma_f32 v140, v72, s86, -v140
	v_fmac_f32_e32 v139, 0x3377d1cf, v70
	v_mul_f32_e32 v143, 0x3f317217, v138
	v_fma_f32 v141, v131, s86, -v141
	v_fmac_f32_e32 v140, 0x3377d1cf, v72
	v_fma_f32 v143, v138, s86, -v143
	v_fmac_f32_e32 v141, 0x3377d1cf, v131
	v_fmac_f32_e32 v140, 0x3f317217, v72
	v_fmac_f32_e32 v143, 0x3377d1cf, v138
	v_fmac_f32_e32 v141, 0x3f317217, v131
	v_fmac_f32_e32 v143, 0x3f317217, v138
	v_mov_b32_e32 v131, v141
	v_min_f32_e32 v132, 0, v132
	v_min_f32_e32 v133, 0, v133
	v_fma_f32 v138, v70, s86, v139
	v_mov_b32_e32 v139, v131
	v_pk_add_f32 v[166:167], v[132:133], v[138:139] neg_lo:[0,1] neg_hi:[0,1]
	v_pk_fma_f32 v[174:175], v[64:65], s[68:69], v[166:167] op_sel_hi:[1,0,1] neg_lo:[1,0,0] neg_hi:[1,0,0]
	v_log_f32_e32 v65, v142
	v_min_f32_e32 v134, 0, v134
	v_min_f32_e32 v135, 0, v135
	v_mov_b32_e32 v141, v143
	v_pk_add_f32 v[164:165], v[134:135], v[140:141] neg_lo:[0,1] neg_hi:[0,1]
	v_mov_b32_e32 v72, v71
	v_pk_fma_f32 v[172:173], v[68:69], s[68:69], v[164:165] op_sel_hi:[1,0,1] neg_lo:[1,0,0] neg_hi:[1,0,0]
	v_mul_f32_e32 v68, 0x3f317217, v65
	v_fma_f32 v70, v65, s86, -v68
	v_pk_mul_f32 v[68:69], v[72:73], s[68:69] op_sel_hi:[1,0]
	v_fmac_f32_e32 v70, 0x3377d1cf, v65
	v_mul_f32_e64 v71, |v68|, s54
	v_exp_f32_e32 v71, v71
	v_fmac_f32_e32 v70, 0x3f317217, v65
	v_mul_f32_e64 v131, |v137|, s54
	v_exp_f32_e32 v131, v131
	v_mov_b32_e32 v65, v70
	v_add_f32_e32 v70, 1.0, v71
	v_mul_f32_e64 v133, |v69|, s54
	v_exp_f32_e32 v133, v133
	v_log_f32_e32 v71, v70
	v_mov_b32_e32 v70, v65
	v_min_f32_e32 v64, 0, v136
	v_mul_f32_e32 v65, 0x3f317217, v71
	v_fma_f32 v65, v71, s86, -v65
	v_fmac_f32_e32 v65, 0x3377d1cf, v71
	v_fmac_f32_e32 v65, 0x3f317217, v71
	v_min_f32_e32 v68, 0, v68
	v_min_f32_e32 v69, 0, v69
	v_add_f32_e32 v71, 1.0, v131
	v_mov_b32_e32 v140, v78
	v_mov_b32_e32 v141, v80
	v_log_f32_e32 v71, v71
	v_mov_b32_e32 v132, v65
	v_min_f32_e32 v65, 0, v137
	v_mul_f32_e32 v131, 0x3f317217, v71
	v_fma_f32 v131, v71, s86, -v131
	v_fmac_f32_e32 v131, 0x3377d1cf, v71
	v_fmac_f32_e32 v131, 0x3f317217, v71
	v_pk_mul_f32 v[142:143], v[140:141], s[68:69] op_sel_hi:[1,0]
	v_mov_b32_e32 v80, v79
	v_mov_b32_e32 v71, v131
	v_mov_b32_e32 v71, v71
	v_add_f32_e32 v131, 1.0, v133
	v_pk_add_f32 v[168:169], v[64:65], v[70:71] neg_lo:[0,1] neg_hi:[0,1]
	v_mov_b32_e32 v65, v76
	v_log_f32_e32 v131, v131
	v_pk_fma_f32 v[176:177], v[66:67], s[68:69], v[168:169] op_sel_hi:[1,0,1] neg_lo:[1,0,0] neg_hi:[1,0,0]
	v_mov_b32_e32 v76, v75
	v_pk_mul_f32 v[144:145], v[80:81], s[68:69] op_sel_hi:[1,0]
	v_mul_f32_e32 v64, 0x3f317217, v131
	v_fma_f32 v70, v131, s86, -v64
	v_mov_b32_e32 v64, v74
	v_pk_mul_f32 v[66:67], v[64:65], s[68:69] op_sel_hi:[1,0]
	v_fmac_f32_e32 v70, 0x3377d1cf, v131
	v_mul_f32_e64 v71, |v66|, s54
	v_exp_f32_e32 v71, v71
	v_min_f32_e32 v66, 0, v66
	v_fma_f32 v133, v131, s86, v70
	v_add_f32_e32 v70, 1.0, v71
	v_pk_add_f32 v[170:171], v[68:69], v[132:133] neg_lo:[0,1] neg_hi:[0,1]
	ds_read_b128 v[132:135], v130 offset:32
	v_log_f32_e32 v70, v70
	v_pk_fma_f32 v[178:179], v[72:73], s[68:69], v[170:171] op_sel_hi:[1,0,1] neg_lo:[1,0,0] neg_hi:[1,0,0]
	v_mul_f32_e64 v73, |v67|, s54
	v_exp_f32_e32 v73, v73
	v_mul_f32_e32 v68, 0x3f317217, v70
	v_fma_f32 v71, v70, s86, -v68
	v_pk_mul_f32 v[68:69], v[76:77], s[68:69] op_sel_hi:[1,0]
	v_fmac_f32_e32 v71, 0x3377d1cf, v70
	v_mul_f32_e64 v72, |v68|, s54
	v_exp_f32_e32 v72, v72
	v_fmac_f32_e32 v71, 0x3f317217, v70
	v_mul_f32_e64 v74, |v69|, s54
	v_exp_f32_e32 v74, v74
	v_mov_b32_e32 v70, v71
	v_add_f32_e32 v71, 1.0, v72
	v_min_f32_e32 v67, 0, v67
	v_min_f32_e32 v68, 0, v68
	v_log_f32_e32 v71, v71
	v_mov_b32_e32 v70, v70
	v_min_f32_e32 v69, 0, v69
	v_mul_f32_e32 v72, 0x3f317217, v71
	v_fma_f32 v72, v71, s86, -v72
	v_fmac_f32_e32 v72, 0x3377d1cf, v71
	v_fmac_f32_e32 v72, 0x3f317217, v71
	s_nop 1
	v_mov_b32_e32 v71, v72
	v_add_f32_e32 v72, 1.0, v73
	s_nop 1
	v_log_f32_e32 v73, v72
	v_mov_b32_e32 v72, v71
	v_mul_f32_e32 v71, 0x3f317217, v73
	v_fma_f32 v71, v73, s86, -v71
	v_fmac_f32_e32 v71, 0x3377d1cf, v73
	v_fmac_f32_e32 v71, 0x3f317217, v73
	s_nop 1
	v_add_f32_e32 v73, 1.0, v74
	v_pk_add_f32 v[180:181], v[66:67], v[70:71] neg_lo:[0,1] neg_hi:[0,1]
	v_mul_f32_e64 v70, |v143|, s54
	v_log_f32_e32 v73, v73
	v_pk_fma_f32 v[184:185], v[64:65], s[68:69], v[180:181] op_sel_hi:[1,0,1] neg_lo:[1,0,0] neg_hi:[1,0,0]
	v_mul_f32_e64 v65, |v142|, s54
	v_exp_f32_e32 v65, v65
	v_mul_f32_e32 v64, 0x3f317217, v73
	v_fma_f32 v64, v73, s86, -v64
	v_fmac_f32_e32 v64, 0x3377d1cf, v73
	v_exp_f32_e32 v131, v70
	v_fma_f32 v73, v73, s86, v64
	v_add_f32_e32 v64, 1.0, v65
	v_mul_f32_e64 v66, |v144|, s54
	v_exp_f32_e32 v66, v66
	v_log_f32_e32 v64, v64
	v_pk_add_f32 v[182:183], v[68:69], v[72:73] neg_lo:[0,1] neg_hi:[0,1]
	v_add_f32_e32 v131, 1.0, v131
	v_pk_fma_f32 v[186:187], v[76:77], s[68:69], v[182:183] op_sel_hi:[1,0,1] neg_lo:[1,0,0] neg_hi:[1,0,0]
	v_mul_f32_e32 v65, 0x3f317217, v64
	v_fma_f32 v65, v64, s86, -v65
	v_fmac_f32_e32 v65, 0x3377d1cf, v64
	v_fmac_f32_e32 v65, 0x3f317217, v64
	v_min_f32_e32 v142, 0, v142
	v_min_f32_e32 v143, 0, v143
	v_mov_b32_e32 v64, v65
	v_add_f32_e32 v65, 1.0, v66
	v_min_f32_e32 v144, 0, v144
	v_mov_b32_e32 v247, v180
	v_log_f32_e32 v68, v65
	v_mov_b32_e32 v146, v64
	ds_read_b128 v[64:67], v130
	v_mul_f32_e32 v69, 0x3f317217, v68
	v_fma_f32 v69, v68, s86, -v69
	v_fmac_f32_e32 v69, 0x3377d1cf, v68
	v_fmac_f32_e32 v69, 0x3f317217, v68
	s_nop 0
	v_mov_b32_e32 v147, v69
	s_waitcnt lgkmcnt(0)
	v_mfma_f32_32x32x16_bf16 v[64:79], v[64:67], v[82:85], 0
	v_mov_b32_e32 v148, v147
	s_nop 0
	ds_read_b128 v[136:139], v130 offset:64
	v_log_f32_e32 v131, v131
	v_mfma_f32_32x32x16_bf16 v[64:79], v[132:135], v[86:89], v[64:79]
	v_mul_f32_e32 v132, 0x3f317217, v131
	v_fma_f32 v147, v131, s86, -v132
	ds_read_b128 v[132:135], v130 offset:96
	v_fmac_f32_e32 v147, 0x3377d1cf, v131
	v_fmac_f32_e32 v147, 0x3f317217, v131
	s_waitcnt lgkmcnt(1)
	v_mfma_f32_32x32x16_bf16 v[64:79], v[136:139], v[90:93], v[64:79]
	v_mul_f32_e64 v137, |v145|, s54
	v_exp_f32_e32 v149, v137
	ds_read_b128 v[136:139], v130 offset:128
	s_waitcnt lgkmcnt(1)
	v_mfma_f32_32x32x16_bf16 v[64:79], v[132:135], v[94:97], v[64:79]
	v_add_f32_e32 v131, 1.0, v149
	v_add_f32_e64 v188, v142, -v146
	v_add_f32_e64 v189, v143, -v147
	v_min_f32_e32 v145, 0, v145
	ds_read_b128 v[132:135], v130 offset:160
	s_waitcnt lgkmcnt(1)
	v_mfma_f32_32x32x16_bf16 v[64:79], v[136:139], v[98:101], v[64:79]
	v_log_f32_e32 v131, v131
	v_pk_fma_f32 v[212:213], v[140:141], s[68:69], v[188:189] op_sel_hi:[1,0,1] neg_lo:[1,0,0] neg_hi:[1,0,0]
	v_mul_f32_e32 v136, 0x3f317217, v131
	v_fma_f32 v140, v131, s86, -v136
	ds_read_b128 v[136:139], v130 offset:192
	s_waitcnt lgkmcnt(1)
	v_mfma_f32_32x32x16_bf16 v[64:79], v[132:135], v[102:105], v[64:79]
	v_fmac_f32_e32 v140, 0x3377d1cf, v131
	s_nop 0
	v_fma_f32 v149, v131, s86, v140
	s_waitcnt lgkmcnt(0)
	v_mfma_f32_32x32x16_bf16 v[64:79], v[136:139], v[106:109], v[64:79]
	v_add_f32_e64 v190, v144, -v148
	v_add_f32_e64 v191, v145, -v149
	ds_read_b64_tr_b16 v[146:147], v207 offset:45056
	ds_read_b64_tr_b16 v[142:143], v207 offset:45120
	ds_read_b64_tr_b16 v[138:139], v207 offset:45184
	ds_read_b64_tr_b16 v[134:135], v207 offset:45248
	ds_read_b64_tr_b16 v[148:149], v207 offset:47616
	ds_read_b64_tr_b16 v[144:145], v207 offset:47680
	ds_read_b64_tr_b16 v[140:141], v207 offset:47744
	ds_read_b64_tr_b16 v[136:137], v207 offset:47808
	ds_read_b64_tr_b16 v[130:131], v207 offset:50176
	ds_read_b64_tr_b16 v[132:133], v207 offset:52736
	v_pk_fma_f32 v[216:217], v[80:81], s[68:69], v[190:191] op_sel_hi:[1,0,1] neg_lo:[1,0,0] neg_hi:[1,0,0]
	v_cmp_lt_i32_e64 s[26:27], 34, v248
	v_mfma_f32_32x32x16_bf16 v[64:79], v[208:211], v[110:113], v[64:79]
	v_cmp_lt_i32_e64 s[30:31], 32, v248
	v_cmp_lt_i32_e64 s[40:41], 33, v248
	s_nop 0
	v_cndmask_b32_e64 v80, 0, v174, s[30:31]
	v_cmp_lt_i32_e64 s[38:39], 35, v248
	v_cndmask_b32_e64 v81, 0, v175, s[26:27]
	v_cndmask_b32_e64 v174, 0, v172, s[40:41]
	v_cndmask_b32_e64 v175, 0, v173, s[38:39]
	v_pk_add_f32 v[80:81], v[80:81], v[174:175]
	v_pk_add_f32 v[172:173], v[80:81], v[80:81] op_sel:[0,1] op_sel_hi:[1,0]
	v_cmp_lt_i32_e64 s[22:23], 40, v248
	v_cmp_lt_i32_e64 s[18:19], 42, v248
	v_cmp_lt_i32_e64 s[28:29], 43, v248
	v_cmp_lt_i32_e64 s[34:35], 41, v248
	v_cmp_lt_i32_e32 vcc, 50, v248
	v_cmp_lt_i32_e64 s[42:43], 48, v248
	v_cmp_lt_i32_e64 s[16:17], 51, v248
	v_cmp_lt_i32_e64 s[44:45], 49, v248
	v_cmp_lt_i32_e64 s[14:15], 58, v248
	v_cmp_lt_i32_e64 s[36:37], 56, v248
	v_cmp_lt_i32_e64 s[20:21], 59, v248
	v_cmp_lt_i32_e64 s[24:25], 57, v248
	v_cndmask_b32_e32 v185, 0, v185, vcc
	v_cndmask_b32_e64 v184, 0, v184, s[42:43]
	v_cndmask_b32_e64 v187, 0, v187, s[16:17]
	v_cndmask_b32_e64 v186, 0, v186, s[44:45]
	v_cndmask_b32_e64 v209, 0, v213, s[14:15]
	v_cndmask_b32_e64 v208, 0, v212, s[36:37]
	v_cndmask_b32_e64 v211, 0, v217, s[20:21]
	v_cndmask_b32_e64 v210, 0, v216, s[24:25]
	v_pk_add_f32 v[184:185], v[184:185], v[186:187]
	v_pk_add_f32 v[208:209], v[208:209], v[210:211]
	v_pk_add_f32 v[240:241], v[184:185], v[184:185] op_sel:[0,1] op_sel_hi:[1,0]
	v_pk_add_f32 v[212:213], v[208:209], v[208:209] op_sel:[0,1] op_sel_hi:[1,0]
	ds_bpermute_b32 v216, v235, v212
	ds_bpermute_b32 v184, v235, v240
	v_mov_b32_e32 v246, v186
	v_mov_b32_e32 v244, v185
	v_cndmask_b32_e64 v177, 0, v177, s[18:19]
	s_waitcnt lgkmcnt(1)
	v_add_f32_e32 v208, v212, v216
	s_waitcnt lgkmcnt(0)
	v_cndmask_b32_e64 v213, 0, v184, s[10:11]
	v_add_f32_e32 v208, v213, v208
	v_add_f32_e32 v245, v162, v208
	v_pk_add_f32 v[246:247], v[246:247], v[244:245]
	v_add_f32_e32 v182, v182, v245
	v_add_f32_e32 v180, v246, v247
	v_mul_f32_e32 v180, 0x3fb8aa3b, v180
	v_exp_f32_e32 v180, v180
	v_add_f32_e32 v182, v185, v182
	v_mul_f32_e32 v182, 0x3fb8aa3b, v182
	v_cndmask_b32_e64 v176, 0, v176, s[22:23]
	v_cndmask_b32_e64 v179, 0, v179, s[28:29]
	v_cndmask_b32_e64 v178, 0, v178, s[34:35]
	v_exp_f32_e32 v182, v182
	v_pk_add_f32 v[176:177], v[176:177], v[178:179]
	v_cndmask_b32_e64 v213, 0, v180, s[42:43]
	v_add_f32_e32 v180, v181, v245
	v_pk_add_f32 v[242:243], v[176:177], v[176:177] op_sel:[0,1] op_sel_hi:[1,0]
	v_add_f32_e32 v180, v187, v180
	ds_bpermute_b32 v80, v235, v172
	ds_bpermute_b32 v176, v235, v242
	v_mul_f32_e32 v180, 0x3fb8aa3b, v180
	v_mov_b32_e32 v185, v240
	v_mov_b32_e32 v217, v212
	v_cndmask_b32_e64 v215, 0, v182, s[44:45]
	v_exp_f32_e32 v239, v180
	v_add_f32_e32 v180, v183, v245
	v_pk_add_f32 v[182:183], v[184:185], v[216:217]
	v_add_f32_e32 v180, 0, v180
	v_add_f32_e32 v181, v242, v183
	v_add_f32_e32 v181, v181, v216
	v_add_f32_e32 v181, v181, v184
	v_cndmask_b32_e64 v173, 0, v216, s[10:11]
	s_waitcnt lgkmcnt(1)
	v_cndmask_b32_e64 v208, 0, v80, s[10:11]
	v_mul_f32_e32 v180, 0x3fb8aa3b, v180
	s_waitcnt lgkmcnt(0)
	v_add_f32_e32 v181, v181, v176
	v_exp_f32_e32 v241, v180
	v_add_f32_e32 v180, v162, v173
	v_add_f32_e32 v173, v183, v216
	v_add_f32_e32 v181, v208, v181
	v_cndmask_b32_e64 v186, 0, v176, s[10:11]
	v_add_f32_e32 v173, v173, v184
	v_add_f32_e32 v185, v162, v181
	v_add_f32_e32 v173, v186, v173
	v_mov_b32_e32 v186, v174
	v_mov_b32_e32 v187, v166
	v_mov_b32_e32 v184, v81
	v_add_f32_e32 v164, v164, v185
	v_pk_add_f32 v[186:187], v[186:187], v[184:185]
	v_add_f32_e32 v81, v81, v164
	v_add_f32_e32 v164, v167, v185
	v_add_f32_e32 v165, v165, v185
	v_add_f32_e32 v166, v186, v187
	v_add_f32_e32 v164, v175, v164
	v_add_f32_e32 v165, 0, v165
	v_mul_f32_e32 v166, 0x3fb8aa3b, v166
	v_mul_f32_e32 v164, 0x3fb8aa3b, v164
	v_mul_f32_e32 v165, 0x3fb8aa3b, v165
	v_exp_f32_e32 v166, v166
	v_exp_f32_e32 v164, v164
	v_exp_f32_e32 v165, v165
	v_mov_b32_e32 v167, v168
	v_cndmask_b32_e64 v174, 0, v166, s[30:31]
	v_cndmask_b32_e64 v175, 0, v164, s[26:27]
	v_cndmask_b32_e64 v181, 0, v165, s[38:39]
	v_add_f32_e32 v165, v162, v173
	v_mov_b32_e32 v166, v178
	v_mov_b32_e32 v164, v177
	v_pk_add_f32 v[166:167], v[166:167], v[164:165]
	v_mul_f32_e32 v81, 0x3fb8aa3b, v81
	v_add_f32_e32 v164, v166, v167
	v_add_f32_e32 v166, v170, v165
	v_add_f32_e32 v167, v169, v165
	v_add_f32_e32 v165, v171, v165
	v_add_f32_e32 v166, v177, v166
	v_add_f32_e32 v167, v179, v167
	v_add_f32_e32 v165, 0, v165
	v_mul_f32_e32 v164, 0x3fb8aa3b, v164
	v_mul_f32_e32 v166, 0x3fb8aa3b, v166
	v_mul_f32_e32 v167, 0x3fb8aa3b, v167
	v_mul_f32_e32 v165, 0x3fb8aa3b, v165
	v_exp_f32_e32 v81, v81
	v_exp_f32_e32 v164, v164
	v_exp_f32_e32 v166, v166
	v_exp_f32_e32 v167, v167
	v_exp_f32_e32 v165, v165
	v_cndmask_b32_e64 v81, 0, v81, s[40:41]
	v_cndmask_b32_e64 v168, 0, v164, s[22:23]
	v_cndmask_b32_e64 v166, 0, v166, s[34:35]
	v_cndmask_b32_e64 v167, 0, v167, s[18:19]
	v_cndmask_b32_e64 v169, 0, v165, s[28:29]
	v_cvt_pk_bf16_f32 v164, v174, v81
	v_cvt_pk_bf16_f32 v165, v175, v181
	v_cvt_pk_bf16_f32 v166, v168, v166
	v_cvt_pk_bf16_f32 v167, v167, v169
	v_mov_b32_e32 v181, v210
	v_mov_b32_e32 v208, v188
	v_mfma_f32_32x32x16_bf16 v[48:63], v[146:149], v[164:167], v[48:63]
	v_add_f32_e64 v146, v180, v208
	v_add_f32_e64 v147, v181, v209
	v_mov_b32_e32 v177, v242
	v_add_f32_e32 v81, v146, v147
	v_mul_f32_e32 v81, 0x3fb8aa3b, v81
	v_exp_f32_e32 v81, v81
	v_cndmask_b32_e32 v146, 0, v239, vcc
	v_cndmask_b32_e64 v81, 0, v81, s[36:37]
	v_mfma_f32_32x32x16_bf16 v[32:47], v[142:145], v[164:167], v[32:47]
	v_add_f32_e32 v143, v180, v190
	v_add_f32_e32 v144, v180, v189
	v_add_f32_e32 v143, v143, v209
	v_mul_f32_e32 v143, 0x3fb8aa3b, v143
	v_exp_f32_e32 v143, v143
	v_cndmask_b32_e64 v142, 0, v241, s[16:17]
	v_mfma_f32_32x32x16_bf16 v[16:31], v[138:141], v[164:167], v[16:31]
	v_add_f32_e32 v139, v180, v191
	v_add_f32_e32 v138, v144, v211
	v_add_f32_e32 v139, 0, v139
	v_mul_f32_e32 v138, 0x3fb8aa3b, v138
	v_mul_f32_e32 v139, 0x3fb8aa3b, v139
	v_exp_f32_e32 v138, v138
	v_exp_f32_e32 v139, v139
	v_mfma_f32_32x32x16_bf16 v[0:15], v[134:137], v[164:167], v[0:15]
	v_cndmask_b32_e64 v136, 0, v143, s[24:25]
	v_cndmask_b32_e64 v137, 0, v138, s[14:15]
	v_cndmask_b32_e64 v138, 0, v139, s[20:21]
	v_cvt_pk_bf16_f32 v134, v213, v215
	v_cvt_pk_bf16_f32 v135, v146, v142
	v_cvt_pk_bf16_f32 v136, v81, v136
	v_cvt_pk_bf16_f32 v137, v137, v138
	ds_read_b64_tr_b16 v[138:139], v207 offset:50240
	ds_read_b64_tr_b16 v[142:143], v207 offset:50304
	ds_read_b64_tr_b16 v[146:147], v207 offset:50368
	ds_read_b64_tr_b16 v[140:141], v207 offset:52800
	ds_read_b64_tr_b16 v[144:145], v207 offset:52864
	ds_read_b64_tr_b16 v[148:149], v207 offset:52928
	v_mfma_f32_32x32x16_bf16 v[48:63], v[130:133], v[134:137], v[48:63]
	v_mov_b32_e32 v130, v64
	v_mov_b32_e32 v131, v68
	v_mul_f32_e64 v132, v130, s68
	v_mul_f32_e64 v133, v131, s68
	v_mov_b32_e32 v81, v172
	v_mul_f32_e64 v64, |v132|, s54
	v_exp_f32_e32 v64, v64
	v_pk_add_f32 v[80:81], v[80:81], v[176:177]
	s_waitcnt lgkmcnt(2)
	v_mfma_f32_32x32x16_bf16 v[32:47], v[138:141], v[134:137], v[32:47]
	v_add_f32_e64 v80, v80, v182
	v_add_f32_e64 v81, v81, v183
	v_add_f32_e32 v64, 1.0, v64
	s_nop 1
	v_log_f32_e32 v138, v64
	v_min_f32_e32 v64, 0, v132
	s_waitcnt lgkmcnt(1)
	v_mfma_f32_32x32x16_bf16 v[16:31], v[142:145], v[134:137], v[16:31]
	v_mul_f32_e64 v143, |v133|, s54
	v_mul_f32_e32 v68, 0x3f317217, v138
	v_fma_f32 v132, v138, s86, -v68
	v_mov_b32_e32 v68, v65
	v_fmac_f32_e32 v132, 0x3377d1cf, v138
	v_fmac_f32_e32 v132, 0x3f317217, v138
	s_waitcnt lgkmcnt(0)
	v_mfma_f32_32x32x16_bf16 v[0:15], v[146:149], v[134:137], v[0:15]
	v_mul_f32_e64 v134, v68, s68
	v_mul_f32_e64 v135, v69, s68
	v_mul_f32_e64 v65, |v134|, s54
	v_exp_f32_e32 v65, v65
	v_mov_b32_e32 v137, v70
	v_exp_f32_e32 v143, v143
	v_min_f32_e32 v134, 0, v134
	v_add_f32_e32 v65, 1.0, v65
	v_add_f32_e32 v143, 1.0, v143
	s_nop 0
	v_log_f32_e32 v65, v65
	s_nop 0
	v_mul_f32_e32 v136, 0x3f317217, v65
	v_fma_f32 v140, v65, s86, -v136
	v_mov_b32_e32 v136, v66
	v_pk_mul_f32 v[138:139], v[136:137], s[68:69] op_sel_hi:[1,0]
	v_fmac_f32_e32 v140, 0x3377d1cf, v65
	v_mul_f32_e64 v66, |v138|, s54
	v_exp_f32_e32 v66, v66
	v_fmac_f32_e32 v140, 0x3f317217, v65
	v_min_f32_e32 v138, 0, v138
	v_add_f32_e32 v66, 1.0, v66
	v_mov_b32_e32 v65, v140
	s_nop 1
	v_log_f32_e32 v142, v66
	v_mov_b32_e32 v70, v67
	v_pk_mul_f32 v[140:141], v[70:71], s[68:69] op_sel_hi:[1,0]
	v_mul_f32_e64 v67, |v140|, s54
	v_exp_f32_e32 v67, v67
	v_mov_b32_e32 v66, v65
	v_mul_f32_e32 v65, 0x3f317217, v142
	v_fma_f32 v65, v142, s86, -v65
	v_fmac_f32_e32 v65, 0x3377d1cf, v142
	v_add_f32_e32 v67, 1.0, v67
	v_min_f32_e32 v140, 0, v140
	s_nop 1
	v_log_f32_e32 v67, v67
	v_fma_f32 v142, v142, s86, v65
	v_mul_f32_e32 v65, 0x3f317217, v67
	v_fma_f32 v65, v67, s86, -v65
	v_fmac_f32_e32 v65, 0x3377d1cf, v67
	s_nop 1
	s_nop 0
	v_log_f32_e32 v143, v143
	v_fma_f32 v144, v67, s86, v65
	v_min_f32_e32 v65, 0, v133
	v_mul_f32_e32 v133, 0x3f317217, v143
	v_fma_f32 v133, v143, s86, -v133
	v_fmac_f32_e32 v133, 0x3377d1cf, v143
	v_fmac_f32_e32 v133, 0x3f317217, v143
	s_nop 1
	v_pk_add_f32 v[64:65], v[64:65], v[132:133] neg_lo:[0,1] neg_hi:[0,1]
	v_mul_f32_e64 v132, |v135|, s54
	v_exp_f32_e32 v132, v132
	v_cmp_lt_i32_e32 vcc, 8, v248
	v_pk_fma_f32 v[130:131], v[130:131], s[68:69], v[64:65] op_sel_hi:[1,0,1] neg_lo:[1,0,0] neg_hi:[1,0,0]
	v_cmp_lt_i32_e64 s[14:15], 0, v248
	v_add_f32_e32 v67, 1.0, v132
	s_nop 0
	v_cndmask_b32_e64 v146, 0, v130, s[14:15]
	v_min_f32_e32 v135, 0, v135
	v_log_f32_e32 v67, v67
	v_cndmask_b32_e32 v147, 0, v131, vcc
	v_mul_f32_e32 v132, 0x3f317217, v67
	v_fma_f32 v132, v67, s86, -v132
	v_fmac_f32_e32 v132, 0x3377d1cf, v67
	v_fmac_f32_e32 v132, 0x3f317217, v67
	s_nop 1
	v_mov_b32_e32 v67, v132
	v_mov_b32_e32 v67, v67
	v_mul_f32_e64 v132, |v139|, s54
	v_pk_add_f32 v[66:67], v[134:135], v[66:67] neg_lo:[0,1] neg_hi:[0,1]
	v_exp_f32_e32 v134, v132
	v_pk_fma_f32 v[68:69], v[68:69], s[68:69], v[66:67] op_sel_hi:[1,0,1] neg_lo:[1,0,0] neg_hi:[1,0,0]
	v_cmp_lt_i32_e64 s[18:19], 1, v248
	v_cmp_lt_i32_e64 s[16:17], 9, v248
	v_min_f32_e32 v139, 0, v139
	v_cndmask_b32_e64 v132, 0, v68, s[18:19]
	v_add_f32_e32 v68, 1.0, v134
	v_cndmask_b32_e64 v133, 0, v69, s[16:17]
	v_log_f32_e32 v68, v68
	v_cmp_lt_i32_e64 s[24:25], 2, v248
	v_mul_f32_e32 v69, 0x3f317217, v68
	v_fma_f32 v69, v68, s86, -v69
	v_fmac_f32_e32 v69, 0x3377d1cf, v68
	v_fmac_f32_e32 v69, 0x3f317217, v68
	s_nop 1
	v_mov_b32_e32 v68, v69
	v_mov_b32_e32 v143, v68
	v_pk_add_f32 v[68:69], v[138:139], v[142:143] neg_lo:[0,1] neg_hi:[0,1]
	v_cmp_lt_i32_e64 s[22:23], 10, v248
	v_pk_fma_f32 v[130:131], v[136:137], s[68:69], v[68:69] op_sel_hi:[1,0,1] neg_lo:[1,0,0] neg_hi:[1,0,0]
	v_mul_f32_e64 v136, |v141|, s54
	v_exp_f32_e32 v136, v136
	v_cndmask_b32_e64 v142, 0, v130, s[24:25]
	v_cndmask_b32_e64 v143, 0, v131, s[22:23]
	v_pk_mul_f32 v[134:135], v[72:73], s[68:69] op_sel_hi:[1,0]
	v_add_f32_e32 v130, 1.0, v136
	v_mul_f32_e64 v138, |v134|, s54
	v_exp_f32_e32 v138, v138
	v_log_f32_e32 v130, v130
	v_cmp_lt_i32_e64 s[34:35], 3, v248
	v_mul_f32_e32 v131, 0x3f317217, v130
	v_fma_f32 v131, v130, s86, -v131
	v_fmac_f32_e32 v131, 0x3377d1cf, v130
	v_fmac_f32_e32 v131, 0x3f317217, v130
	v_min_f32_e32 v134, 0, v134
	v_min_f32_e32 v141, 0, v141
	v_mov_b32_e32 v130, v131
	v_cmp_lt_i32_e64 s[26:27], 11, v248
	v_add_f32_e32 v136, 1.0, v138
	v_mov_b32_e32 v145, v130
	v_pk_add_f32 v[130:131], v[140:141], v[144:145] neg_lo:[0,1] neg_hi:[0,1]
	v_log_f32_e32 v136, v136
	v_mul_f32_e64 v138, |v135|, s54
	v_exp_f32_e32 v138, v138
	v_min_f32_e32 v135, 0, v135
	v_mul_f32_e32 v137, 0x3f317217, v136
	v_fma_f32 v137, v136, s86, -v137
	v_fmac_f32_e32 v137, 0x3377d1cf, v136
	v_fmac_f32_e32 v137, 0x3f317217, v136
	v_cmp_lt_i32_e64 s[36:37], 16, v248
	v_mov_b32_e32 v136, v137
	v_add_f32_e32 v137, 1.0, v138
	v_pk_fma_f32 v[70:71], v[70:71], s[68:69], v[130:131] op_sel_hi:[1,0,1] neg_lo:[1,0,0] neg_hi:[1,0,0]
	s_nop 0
	v_log_f32_e32 v137, v137
	v_mov_b32_e32 v136, v136
	v_cndmask_b32_e64 v71, 0, v71, s[26:27]
	v_mul_f32_e32 v138, 0x3f317217, v137
	v_fma_f32 v138, v137, s86, -v138
	v_fmac_f32_e32 v138, 0x3377d1cf, v137
	v_fmac_f32_e32 v138, 0x3f317217, v137
	v_cndmask_b32_e64 v70, 0, v70, s[34:35]
	s_nop 0
	v_mov_b32_e32 v137, v138
	v_mov_b32_e32 v137, v137
	v_pk_add_f32 v[134:135], v[134:135], v[136:137] neg_lo:[0,1] neg_hi:[0,1]
	v_pk_mul_f32 v[136:137], v[74:75], s[68:69] op_sel_hi:[1,0]
	v_mul_f32_e64 v139, |v136|, s54
	v_exp_f32_e32 v139, v139
	v_cmp_lt_i32_e64 s[20:21], 17, v248
	v_mul_f32_e64 v140, |v137|, s54
	v_exp_f32_e32 v140, v140
	v_add_f32_e32 v138, 1.0, v139
	v_min_f32_e32 v136, 0, v136
	v_min_f32_e32 v137, 0, v137
	v_log_f32_e32 v138, v138
	v_pk_fma_f32 v[72:73], v[72:73], s[68:69], v[134:135] op_sel_hi:[1,0,1] neg_lo:[1,0,0] neg_hi:[1,0,0]
	v_mul_f32_e32 v139, 0x3f317217, v138
	v_fma_f32 v139, v138, s86, -v139
	v_fmac_f32_e32 v139, 0x3377d1cf, v138
	v_fmac_f32_e32 v139, 0x3f317217, v138
	v_cndmask_b32_e64 v73, 0, v73, s[20:21]
	v_cndmask_b32_e64 v72, 0, v72, s[36:37]
	v_mov_b32_e32 v138, v139
	v_add_f32_e32 v139, 1.0, v140
	s_nop 1
	v_log_f32_e32 v139, v139
	v_mov_b32_e32 v138, v138
	v_mul_f32_e32 v140, 0x3f317217, v139
	v_fma_f32 v140, v139, s86, -v140
	v_fmac_f32_e32 v140, 0x3377d1cf, v139
	v_fmac_f32_e32 v140, 0x3f317217, v139
	s_nop 1
	v_mov_b32_e32 v139, v140
	v_mov_b32_e32 v139, v139
	v_cmp_lt_i32_e64 s[30:31], 18, v248
	v_pk_add_f32 v[140:141], v[142:143], v[70:71]
	v_mov_b32_e32 v142, v76
	v_mov_b32_e32 v143, v78
	v_pk_mul_f32 v[144:145], v[142:143], s[68:69] op_sel_hi:[1,0]
	v_pk_add_f32 v[136:137], v[136:137], v[138:139] neg_lo:[0,1] neg_hi:[0,1]
	v_mul_f32_e64 v76, |v144|, s54
	v_exp_f32_e32 v78, v76
	v_pk_fma_f32 v[74:75], v[74:75], s[68:69], v[136:137] op_sel_hi:[1,0,1] neg_lo:[1,0,0] neg_hi:[1,0,0]
	v_cmp_lt_i32_e64 s[28:29], 19, v248
	v_cndmask_b32_e64 v138, 0, v74, s[30:31]
	v_mul_f32_e64 v149, |v145|, s54
	v_cndmask_b32_e64 v139, 0, v75, s[28:29]
	v_pk_add_f32 v[74:75], v[146:147], v[132:133]
	v_exp_f32_e32 v149, v149
	v_pk_add_f32 v[146:147], v[74:75], v[140:141]
	v_add_f32_e32 v74, 1.0, v78
	ds_bpermute_b32 v148, v235, v147
	ds_bpermute_b32 v76, v235, v146
	v_log_f32_e32 v75, v74
	v_mov_b32_e32 v74, v73
	v_mul_f32_e32 v78, 0x3f317217, v75
	v_pk_add_f32 v[164:165], v[72:73], v[74:75]
	v_min_f32_e32 v74, 0, v144
	v_fma_f32 v144, v75, s86, -v78
	v_mov_b32_e32 v78, v77
	v_pk_mul_f32 v[166:167], v[78:79], s[68:69] op_sel_hi:[1,0]
	v_fmac_f32_e32 v144, 0x3377d1cf, v75
	v_mul_f32_e64 v77, |v166|, s54
	v_exp_f32_e32 v77, v77
	v_fmac_f32_e32 v144, 0x3f317217, v75
	v_min_f32_e32 v166, 0, v166
	v_add_f32_e32 v77, 1.0, v77
	v_mov_b32_e32 v75, v144
	v_cmp_lt_i32_e64 s[42:43], 24, v248
	v_log_f32_e32 v77, v77
	v_mov_b32_e32 v144, v75
	v_mul_f32_e32 v75, 0x3f317217, v77
	v_fma_f32 v75, v77, s86, -v75
	v_fmac_f32_e32 v75, 0x3377d1cf, v77
	s_nop 1
	v_fma_f32 v168, v77, s86, v75
	v_add_f32_e32 v75, 1.0, v149
	s_nop 0
	v_log_f32_e32 v77, v75
	v_min_f32_e32 v75, 0, v145
	v_mul_f32_e32 v145, 0x3f317217, v77
	v_fma_f32 v145, v77, s86, -v145
	v_fmac_f32_e32 v145, 0x3377d1cf, v77
	v_fmac_f32_e32 v145, 0x3f317217, v77
	s_nop 1
	v_mov_b32_e32 v77, v145
	v_mov_b32_e32 v145, v77
	v_mul_f32_e64 v77, |v167|, s54
	v_exp_f32_e32 v77, v77
	v_pk_add_f32 v[74:75], v[74:75], v[144:145] neg_lo:[0,1] neg_hi:[0,1]
	v_min_f32_e32 v167, 0, v167
	v_cmp_lt_i32_e64 s[38:39], 26, v248
	v_add_f32_e32 v77, 1.0, v77
	v_log_f32_e32 v77, v77
	v_pk_fma_f32 v[142:143], v[142:143], s[68:69], v[74:75] op_sel_hi:[1,0,1] neg_lo:[1,0,0] neg_hi:[1,0,0]
	v_mul_f32_e32 v144, 0x3f317217, v77
	v_fma_f32 v144, v77, s86, -v144
	v_fmac_f32_e32 v144, 0x3377d1cf, v77
	v_fmac_f32_e32 v144, 0x3f317217, v77
	v_cndmask_b32_e64 v143, 0, v143, s[38:39]
	v_cndmask_b32_e64 v142, 0, v142, s[42:43]
	v_mov_b32_e32 v77, v144
	v_mov_b32_e32 v169, v77
	v_pk_add_f32 v[144:145], v[166:167], v[168:169] neg_lo:[0,1] neg_hi:[0,1]
	v_cmp_lt_i32_e64 s[40:41], 27, v248
	v_pk_fma_f32 v[78:79], v[78:79], s[68:69], v[144:145] op_sel_hi:[1,0,1] neg_lo:[1,0,0] neg_hi:[1,0,0]
	v_cmp_lt_i32_e64 s[44:45], 25, v248
	v_cndmask_b32_e64 v167, 0, v79, s[40:41]
	v_mov_b32_e32 v168, v132
	v_cndmask_b32_e64 v166, 0, v78, s[44:45]
	v_mov_b32_e32 v132, v139
	v_pk_add_f32 v[142:143], v[142:143], v[166:167]
	v_pk_add_f32 v[170:171], v[138:139], v[132:133]
	v_mov_b32_e32 v165, v142
	v_mov_b32_e32 v171, v143
	v_pk_add_f32 v[164:165], v[164:165], v[170:171]
	ds_bpermute_b32 v149, v235, v165
	ds_bpermute_b32 v77, v235, v164
	v_pk_add_f32 v[78:79], v[146:147], v[146:147] op_sel_hi:[0,1]
	v_mov_b32_e32 v169, v64
	v_mov_b32_e32 v64, v133
	v_pk_add_f32 v[132:133], v[164:165], v[164:165] op_sel:[0,1] op_sel_hi:[1,0]
	s_waitcnt lgkmcnt(1)
	v_add_f32_e32 v142, v165, v149
	s_waitcnt lgkmcnt(0)
	v_cndmask_b32_e64 v146, 0, v77, s[10:11]
	v_add_f32_e32 v142, v146, v142
	v_add_f32_e32 v146, v132, v149
	v_add_f32_e32 v147, v147, v132
	v_add_f32_e32 v146, v146, v77
	v_cndmask_b32_e64 v163, 0, v148, s[10:11]
	v_add_f32_e32 v147, v147, v149
	v_add_f32_e32 v146, v163, v146
	v_add_f32_e32 v147, v147, v77
	v_cndmask_b32_e64 v163, 0, v76, s[10:11]
	v_pk_add_f32 v[76:77], v[76:77], v[148:149]
	v_mov_b32_e32 v78, v80
	v_add_f32_e32 v147, v147, v148
	v_pk_add_f32 v[76:77], v[76:77], v[76:77] op_sel_hi:[0,1]
	v_pk_mov_b32 v[80:81], v[80:81], v[132:133] op_sel:[1,0]
	v_add_f32_e32 v147, v163, v147
	v_pk_add_f32 v[78:79], v[78:79], v[80:81]
	v_mov_b32_e32 v163, v77
	v_pk_add_f32 v[80:81], v[162:163], v[78:79]
	v_mov_b32_e32 v76, v140
	v_add_f32_e32 v77, v80, v147
	v_pk_add_f32 v[78:79], v[168:169], v[76:77]
	v_add_f32_e32 v68, v68, v77
	v_add_f32_e32 v76, v78, v79
	v_mul_f32_e32 v76, 0x3fb8aa3b, v76
	v_exp_f32_e32 v76, v76
	v_add_f32_e32 v66, v66, v77
	v_add_f32_e32 v68, v70, v68
	v_add_f32_e32 v70, v130, v77
	v_cndmask_b32_e64 v78, 0, v76, s[14:15]
	v_add_f32_e32 v77, v80, v146
	v_mov_b32_e32 v76, v141
	v_add_f32_e32 v66, v140, v66
	v_pk_add_f32 v[64:65], v[64:65], v[76:77]
	v_mul_f32_e32 v66, 0x3fb8aa3b, v66
	v_add_f32_e32 v64, v64, v65
	v_add_f32_e32 v65, v67, v77
	v_exp_f32_e32 v66, v66
	v_add_f32_e32 v65, v141, v65
	v_mul_f32_e32 v64, 0x3fb8aa3b, v64
	v_mul_f32_e32 v65, 0x3fb8aa3b, v65
	v_exp_f32_e32 v64, v64
	v_exp_f32_e32 v65, v65
	v_cndmask_b32_e64 v79, 0, v66, s[18:19]
	v_add_f32_e32 v66, v69, v77
	v_add_f32_e32 v66, v71, v66
	v_mul_f32_e32 v66, 0x3fb8aa3b, v66
	v_cndmask_b32_e32 v71, 0, v64, vcc
	v_cndmask_b32_e64 v76, 0, v65, s[16:17]
	v_add_f32_e32 v171, v80, v142
	v_pk_mov_b32 v[64:65], v[72:73], v[134:135] op_sel:[1,0]
	v_exp_f32_e32 v66, v66
	v_add_f32_e32 v67, v131, v77
	v_pk_add_f32 v[64:65], v[64:65], v[170:171]
	v_add_f32_e32 v67, 0, v67
	v_add_f32_e32 v64, v64, v65
	v_add_f32_e32 v65, v135, v171
	v_mul_f32_e32 v67, 0x3fb8aa3b, v67
	v_mul_f32_e32 v64, 0x3fb8aa3b, v64
	v_add_f32_e32 v65, v170, v65
	v_exp_f32_e32 v67, v67
	v_exp_f32_e32 v64, v64
	v_mul_f32_e32 v65, 0x3fb8aa3b, v65
	v_add_f32_e32 v70, 0, v70
	v_cndmask_b32_e64 v77, 0, v66, s[22:23]
	v_exp_f32_e32 v140, v65
	v_add_f32_e32 v65, v136, v171
	v_add_f32_e32 v66, v137, v171
	v_mul_f32_e32 v68, 0x3fb8aa3b, v68
	v_mul_f32_e32 v70, 0x3fb8aa3b, v70
	v_add_f32_e32 v65, v139, v65
	v_add_f32_e32 v66, 0, v66
	v_exp_f32_e32 v68, v68
	v_exp_f32_e32 v70, v70
	v_mul_f32_e32 v65, 0x3fb8aa3b, v65
	v_mul_f32_e32 v66, 0x3fb8aa3b, v66
	v_cndmask_b32_e64 v131, 0, v67, s[26:27]
	v_exp_f32_e32 v139, v66
	v_exp_f32_e32 v141, v65
	v_cndmask_b32_e64 v146, 0, v64, s[36:37]
	ds_read_b64_tr_b16 v[64:65], v207 offset:34816
	ds_read_b64_tr_b16 v[66:67], v207 offset:37376
	v_cndmask_b32_e64 v138, 0, v149, s[10:11]
	v_add_f32_e32 v72, v80, v138
	v_mov_b32_e32 v73, v166
	v_mov_b32_e32 v142, v74
	v_cndmask_b32_e64 v130, 0, v68, s[24:25]
	v_cndmask_b32_e64 v70, 0, v70, s[34:35]
	v_pk_add_f32 v[68:69], v[72:73], v[142:143]
	v_cndmask_b32_e64 v74, 0, v139, s[28:29]
	v_add_f32_e32 v73, v68, v69
	v_cvt_pk_bf16_f32 v68, v78, v79
	v_cvt_pk_bf16_f32 v69, v130, v70
	v_cvt_pk_bf16_f32 v70, v71, v76
	v_cvt_pk_bf16_f32 v71, v77, v131
	ds_read_b64_tr_b16 v[76:77], v207 offset:34880
	ds_read_b64_tr_b16 v[130:131], v207 offset:34944
	ds_read_b64_tr_b16 v[134:135], v207 offset:35008
	ds_read_b64_tr_b16 v[78:79], v207 offset:37440
	ds_read_b64_tr_b16 v[132:133], v207 offset:37504
	ds_read_b64_tr_b16 v[136:137], v207 offset:37568
	s_waitcnt lgkmcnt(6)
	v_mfma_f32_32x32x16_bf16 v[48:63], v[64:67], v[68:71], v[48:63]
	v_mul_f32_e32 v64, 0x3fb8aa3b, v73
	v_exp_f32_e32 v64, v64
	v_add_f32_e32 v65, v72, v75
	v_add_f32_e32 v65, v65, v167
	v_mul_f32_e32 v65, 0x3fb8aa3b, v65
	v_cndmask_b32_e64 v139, 0, v64, s[42:43]
	v_add_f32_e32 v64, v72, v144
	v_exp_f32_e32 v75, v65
	v_add_f32_e32 v65, v72, v145
	v_add_f32_e32 v64, v64, v143
	v_add_f32_e32 v65, 0, v65
	v_mul_f32_e32 v64, 0x3fb8aa3b, v64
	v_mul_f32_e32 v65, 0x3fb8aa3b, v65
	v_exp_f32_e32 v64, v64
	v_exp_f32_e32 v72, v65
	s_waitcnt lgkmcnt(2)
	v_mfma_f32_32x32x16_bf16 v[32:47], v[76:79], v[68:71], v[32:47]
	v_cndmask_b32_e64 v73, 0, v140, s[20:21]
	v_cndmask_b32_e64 v138, 0, v141, s[30:31]
	v_cndmask_b32_e64 v76, 0, v64, s[44:45]
	v_cndmask_b32_e64 v72, 0, v72, s[40:41]
	ds_read_b64_tr_b16 v[64:65], v207 offset:39936
	ds_read_b64_tr_b16 v[66:67], v207 offset:42496
	v_add_f32_e32 v162, v80, v81
	s_mov_b32 s14, 0xc2480000
	s_waitcnt lgkmcnt(3)
	v_mfma_f32_32x32x16_bf16 v[16:31], v[130:133], v[68:71], v[16:31]
	v_cmp_gt_f32_e32 vcc, s14, v162
	s_cmp_eq_u64 vcc, exec
	s_cselect_b64 s[14:15], -1, 0
	s_waitcnt lgkmcnt(2)
	v_mfma_f32_32x32x16_bf16 v[0:15], v[134:137], v[68:71], v[0:15]
	v_cndmask_b32_e64 v71, 0, v75, s[38:39]
	v_cvt_pk_bf16_f32 v68, v146, v73
	v_cvt_pk_bf16_f32 v69, v138, v74
	v_cvt_pk_bf16_f32 v70, v139, v76
	v_cvt_pk_bf16_f32 v71, v71, v72
	ds_read_b64_tr_b16 v[72:73], v207 offset:40000
	ds_read_b64_tr_b16 v[76:77], v207 offset:40064
	ds_read_b64_tr_b16 v[130:131], v207 offset:40128
	ds_read_b64_tr_b16 v[74:75], v207 offset:42560
	ds_read_b64_tr_b16 v[78:79], v207 offset:42624
	ds_read_b64_tr_b16 v[132:133], v207 offset:42688
	s_waitcnt lgkmcnt(6)
	v_mfma_f32_32x32x16_bf16 v[48:63], v[64:67], v[68:71], v[48:63]
	s_waitcnt lgkmcnt(2)
	v_mfma_f32_32x32x16_bf16 v[32:47], v[72:75], v[68:71], v[32:47]
	s_waitcnt lgkmcnt(1)
	v_mfma_f32_32x32x16_bf16 v[16:31], v[76:79], v[68:71], v[16:31]
	s_waitcnt lgkmcnt(0)
	v_mfma_f32_32x32x16_bf16 v[0:15], v[130:133], v[68:71], v[0:15]
